# attention unit loop: loop-head wait for the prefetched ticket and the decode's vmcnt(1) (lam load) moved to one wait before the loop; from the second unit on they only drained the map-0 waves' 64 epil
# speedup vs baseline: 1.0061x; 1.0058x over previous
; __global__ void __launch_bounds__(NWAVES * 64, 2) hymba_fwd(Args args) {
;     ...
;         const float lam = ((const float*)ctl)[CW_LAM];
;         constexpr int NU = 512 + 1024;
;         for (;;) {
;             if (tid == 0) MISC[0] = atomicAdd(ctl + CW_QCTR, 1u);
;             __syncthreads();
;             const int u = (int)MISC[0];
.Lattn_q0:
	s_or_b64 exec, exec, s[98:99]
	s_waitcnt vmcnt(0)
	s_branch .LBB0_293

; __global__ void __launch_bounds__(NWAVES * 64, 2) hymba_fwd(Args args) {
;     ...
;             if (tid == 0) MISC[0] = atomicAdd(ctl + CW_QCTR, 1u);
;             __syncthreads();
;             const int u = (int)MISC[0];
.LBB0_293:
	s_and_saveexec_b64 s[0:1], s[22:23]
	s_cbranch_execz .LBB0_297
	v_mov_b32_e32 v1, s15
	ds_write_b32 v1, v175

; __global__ void __launch_bounds__(NWAVES * 64, 2) hymba_fwd(Args args) {
;     ...
;             if (u < 512) { h = 3 - (u >> 7); q0 = (u & 127) * 128; seq0 = NPROMPT; nt = SS / 64; sq = 16; }
;             else { const int v = u - 512; h = 3 - (v >> 8); sq = (v >> 4) & 15; q0 = (v & 15) * 128; seq0 = sq * SP; nt = SP / 64; }
;             const float slope = (h == 0) ? 0.25f : (h == 1) ? 0.0625f : (h == 2) ? 0.015625f : 0.00390625f;
.LBB0_300:
	s_cmp_gt_i32 s24, 2
	v_mov_b32_e32 v18, 0x3e800000
	s_cbranch_scc0 .LBB0_303
	s_branch .LBB0_307

; __global__ void __launch_bounds__(NWAVES * 64, 2) hymba_fwd(Args args) {
;     ...
;             if (u < 512) { h = 3 - (u >> 7); q0 = (u & 127) * 128; seq0 = NPROMPT; nt = SS / 64; sq = 16; }
;             else { const int v = u - 512; h = 3 - (v >> 8); sq = (v >> 4) & 15; q0 = (v & 15) * 128; seq0 = sq * SP; nt = SP / 64; }
;             const float slope = (h == 0) ? 0.25f : (h == 1) ? 0.0625f : (h == 2) ? 0.015625f : 0.00390625f;
.LBB0_302:
	s_lshl_b32 s0, s25, 7
	s_ashr_i32 s24, s25, 7
	s_and_b32 s31, s0, 0x3f80
	s_mov_b32 s35, 0x8000
	s_movk_i32 s3, 0x100
	s_mov_b64 s[0:1], 0x100
	s_cmp_gt_i32 s24, 2
	v_mov_b32_e32 v18, 0x3e800000
	s_cbranch_scc1 .LBB0_307
